# mode0 attn: K/V loads issued at end of previous body via SGPR-base addressing (no VALU address math), MFMA-first tile head with C-prefill v_movs moved into early MFMA gaps
# speedup vs baseline: 1.0051x; 1.0051x over previous
; __device__ __forceinline__ float swapmax(float m) { auto rr = __builtin_amdgcn_permlane32_swap(__float_as_uint(m), __float_as_uint(m), false, false); return fmaxf(__uint_as_float(rr[0]), __uint_as_float(rr[1])); }
; #define A2_TILE_BIAS(t, cbv, nearv) do { cbv = 0.f; nearv = (MODE == 2); if (MODE == 0) { const int ks_ = 64 * (t); const int maxrel_ = ks_ + 63 - qslot0, minrel_ = ks_ - (qslot0 + 31); \
;         const bool lf_ = maxrel_ <= -91, rt_ = minrel_ >= 91; cbv = lf_ ? tabL : (rt_ ? tabR : 0.f); nearv = !(lf_ || rt_); } } while (0)
; template <int MODE> __device__ __forceinline__ void attn_unit4(LAS unsigned char* lds, const int uidx, const AttnArgs& A) {
;     ...
;     float mref;
;     { float mx = fmaxf(s0[0], s1[0]);
; #pragma unroll
;       for (int r = 1; r < 16; ++r) mx = fmaxf(mx, fmaxf(s0[r], s1[r]));
;       mx = swapmax(mx) + cbc; mref = fmaxf(mx, -30.0f);
;       const float sh = cbc - mref;
; #pragma unroll
;       for (int r = 0; r < 16; ++r) { s0[r] += sh; s1[r] += sh; } }
;     constexpr bool USE_NEGC = (MODE != 0);
;     f32x16 negc;
;     { float cb1; bool nr1; A2_TILE_BIAS(t0 + 1, cb1, nr1); const float nv = cb1 - mref;
; #pragma unroll
;       for (int r = 0; r < 16; ++r) { n0[r] = nv; n1[r] = nv; negc[r] = nv; } }
;     int vs_prev = 2, vs_cur = 0, vs_next = 1;
; #pragma unroll
;     for (int c = 0; c < 4; ++c) pk[c] = (u32x4){0u, 0u, 0u, 0u};
.LBB0_983:
	v_cndmask_b32_e32 v3, 0, v195, vcc
	v_max_f32_e32 v2, v2, v2
	v_max_f32_e32 v0, v0, v0
	v_cndmask_b32_e64 v3, v3, v194, s[0:1]
	v_max_f32_e32 v0, v0, v2
	v_add_f32_e32 v0, v3, v0
	v_max_f32_e32 v197, 0xc1f00000, v0
	v_cndmask_b32_e64 v0, 0, v195, s[6:7]
	v_cndmask_b32_e64 v0, v0, v194, s[4:5]
	s_movk_i32 s0, 0x140
	v_and_b32_e32 v177, 63, v19
	v_sub_f32_e32 v82, v0, v197
	v_sub_f32_e32 v0, v3, v197
	v_mov_b32_e32 v19, v10
	v_mov_b32_e32 v4, v11
	v_mov_b32_e32 v5, v12
	v_mov_b32_e32 v6, v13
	v_mov_b32_e32 v7, v14
	v_mov_b32_e32 v8, v15
	v_mov_b32_e32 v9, v16
	v_mad_u64_u32 v[178:179], s[0:1], v22, s0, v[20:21]
	s_mulk_i32 s37, 0x2080
	v_pk_add_f32 v[2:3], v[18:19], v[0:1] op_sel_hi:[1,0]
	v_pk_add_f32 v[4:5], v[4:5], v[0:1] op_sel_hi:[1,0]
	v_pk_add_f32 v[6:7], v[6:7], v[0:1] op_sel_hi:[1,0]
	v_pk_add_f32 v[8:9], v[8:9], v[0:1] op_sel_hi:[1,0]
	v_add_f32_e32 v81, v17, v0
	s_add_i32 s70, s71, 0x7a
	s_addk_i32 s71, 0xffb9
	v_or_b32_e32 v0, s37, v181
	s_lshl_b32 s0, s36, 7
	v_sub_u32_e32 v0, v0, v21
	s_add_u32 s1, s73, s8
	v_subrev_u32_e32 v0, s52, v0
	s_addc_u32 s4, s53, s9
	v_mov_b32_e32 v14, v1
	v_mov_b32_e32 v15, v1
	v_mov_b32_e32 v98, v2
	v_mov_b32_e32 v99, v2
	v_mov_b32_e32 v100, v2
	v_mov_b32_e32 v101, v2
	v_mov_b32_e32 v102, v2
	v_mov_b32_e32 v103, v2
	v_mov_b32_e32 v104, v2
	v_mov_b32_e32 v105, v2
	v_mov_b32_e32 v106, v2
	v_mov_b32_e32 v107, v2
	v_mov_b32_e32 v108, v2
	v_mov_b32_e32 v109, v2
	v_mov_b32_e32 v110, v2
	v_mov_b32_e32 v111, v2
	v_mov_b32_e32 v112, v2
	v_mov_b32_e32 v113, v2
	v_mov_b32_e32 v66, v2
	v_mov_b32_e32 v67, v2
	v_mov_b32_e32 v68, v2
	v_mov_b32_e32 v69, v2
	v_mov_b32_e32 v70, v2
	v_mov_b32_e32 v71, v2
	v_mov_b32_e32 v72, v2
	v_mov_b32_e32 v73, v2
	v_mov_b32_e32 v74, v3
	v_mov_b32_e32 v75, v4
	v_mov_b32_e32 v76, v5
	v_mov_b32_e32 v77, v6
	v_mov_b32_e32 v78, v7
	v_mov_b32_e32 v79, v8
	v_mov_b32_e32 v80, v9
	v_subrev_u32_e32 v179, s0, v0
	s_add_u32 s8, s16, s1
	v_mov_b32_e32 v0, v1
	v_mov_b32_e32 v2, v1
	v_mov_b32_e32 v3, v1
	v_mov_b32_e32 v4, v1
	v_mov_b32_e32 v5, v1
	v_mov_b32_e32 v6, v1
	v_mov_b32_e32 v7, v1
	v_mov_b32_e32 v8, v1
	v_mov_b32_e32 v9, v1
	v_mov_b32_e32 v10, v1
	v_mov_b32_e32 v11, v1
	v_mov_b32_e32 v12, v1
	v_mov_b32_e32 v13, v1
	v_mov_b64_e32 v[64:65], v[14:15]
	v_mov_b64_e32 v[48:49], v[14:15]
	v_mov_b64_e32 v[32:33], v[14:15]
	s_addc_u32 s9, s17, s4
	s_sub_i32 s1, s37, s52
	v_mov_b64_e32 v[62:63], v[12:13]
	v_mov_b64_e32 v[60:61], v[10:11]
	v_mov_b64_e32 v[58:59], v[8:9]
	v_mov_b64_e32 v[56:57], v[6:7]
	v_mov_b64_e32 v[54:55], v[4:5]
	v_mov_b64_e32 v[52:53], v[2:3]
	v_mov_b64_e32 v[50:51], v[0:1]
	v_mov_b64_e32 v[46:47], v[12:13]
	v_mov_b64_e32 v[44:45], v[10:11]
	v_mov_b64_e32 v[42:43], v[8:9]
	v_mov_b64_e32 v[40:41], v[6:7]
	v_mov_b64_e32 v[38:39], v[4:5]
	v_mov_b64_e32 v[36:37], v[2:3]
	v_mov_b64_e32 v[34:35], v[0:1]
	v_mov_b64_e32 v[30:31], v[12:13]
	v_mov_b64_e32 v[28:29], v[10:11]
	v_mov_b64_e32 v[26:27], v[8:9]
	v_mov_b64_e32 v[24:25], v[6:7]
	v_mov_b64_e32 v[22:23], v[4:5]
	v_mov_b64_e32 v[20:21], v[2:3]
	v_mov_b64_e32 v[18:19], v[0:1]
	v_mov_b64_e32 v[16:17], v[14:15]
	s_mov_b32 s72, 1
	s_sub_i32 s73, s1, s0
	s_mov_b32 s74, 0
	s_mov_b32 s0, 2
	v_mov_b32_e32 v180, 1.0
	v_mov_b32_e32 v198, 0
	s_movk_i32 s75, 0x100
	v_mov_b32_e32 v142, 0
	v_mov_b32_e32 v143, 0
	v_mov_b32_e32 v144, 0
	v_mov_b32_e32 v145, 0
	v_mov_b32_e32 v138, 0
	v_mov_b32_e32 v139, 0
	v_mov_b32_e32 v140, 0
	v_mov_b32_e32 v141, 0
	v_mov_b32_e32 v134, 0
	v_mov_b32_e32 v135, 0
	v_mov_b32_e32 v136, 0
	v_mov_b32_e32 v137, 0
	v_mov_b32_e32 v130, 0
	v_mov_b32_e32 v131, 0
	v_mov_b32_e32 v132, 0
	v_mov_b32_e32 v133, 0
	v_mov_b64_e32 v[14:15], v[12:13]
	v_mov_b64_e32 v[12:13], v[10:11]
	v_mov_b64_e32 v[10:11], v[8:9]
	v_mov_b64_e32 v[8:9], v[6:7]
	v_mov_b64_e32 v[6:7], v[4:5]
	v_mov_b64_e32 v[4:5], v[2:3]
	v_mov_b64_e32 v[2:3], v[0:1]
	v_mov_b32_e32 v0, 1.0
	s_add_u32 s84, s8, s88
	s_addc_u32 s85, s9, 0
	s_add_u32 s98, s8, s67
	s_addc_u32 s99, s9, 0
	global_load_dwordx4 v[228:231], v168, s[84:85] offset:1024
	global_load_dwordx4 v[232:235], v170, s[84:85] offset:1024
	global_load_dwordx4 v[236:239], v168, s[98:99] offset:2048
	global_load_dwordx4 v[240:243], v170, s[98:99] offset:2048
	s_mov_b32 s76, 1
	s_mov_b32 s77, s74
	s_mov_b32 s74, s0
	v_cmp_neq_f32_e32 vcc, 1.0, v180
	s_cbranch_vccz .LBB0_985

.LBB0_985:
	s_waitcnt lgkmcnt(3)
	v_mfma_f32_32x32x16_bf16 v[50:65], v[158:161], v[142:145], v[50:65]
	s_add_i32 s52, s73, s75
	s_add_i32 s0, s75, 0xffffff80
	s_add_i32 s37, s52, 0xffffff80
	s_cmp_lt_i32 s0, s70
	s_cselect_b64 s[6:7], -1, 0
	s_sub_i32 s0, s52, 64
	s_cmpk_gt_i32 s0, 0xff66
	s_cselect_b64 s[0:1], -1, 0
	s_add_i32 s36, s52, 0xffffffa1
	s_cmpk_gt_i32 s36, 0x5a
	s_cselect_b64 s[4:5], -1, 0
	s_cmp_gt_u32 s76, 1
	s_cselect_b32 s53, s74, s77
	s_mulk_i32 s53, 0x5000
	s_cmpk_gt_i32 s37, 0xff66
	v_add_u32_e32 v180, s53, v192
	s_cselect_b64 s[78:79], -1, 0
	v_add_u32_e32 v199, 0xc800, v180
	s_and_b64 s[6:7], s[78:79], s[6:7]
	ds_read_b64_tr_b16 v[200:201], v180 offset:56320
	ds_read_b64_tr_b16 v[202:203], v180 offset:58880
	s_mul_i32 s78, s72, 0x5000
	s_add_i32 s37, s78, 0
	v_mov_b32_e32 v83, v82
	v_mov_b32_e32 v84, v82
	v_mov_b32_e32 v85, v82
	v_mov_b32_e32 v86, v82
	s_waitcnt lgkmcnt(4)
	v_mfma_f32_32x32x16_bf16 v[34:49], v[154:157], v[142:145], v[34:49]
	ds_read_b64_tr_b16 v[204:205], v180 offset:56384
	ds_read_b64_tr_b16 v[206:207], v180 offset:58944
	v_mov_b32_e32 v87, v82
	v_mov_b32_e32 v88, v82
	v_mov_b32_e32 v89, v82
	v_mov_b32_e32 v90, v82
	s_waitcnt lgkmcnt(5)
	v_mfma_f32_32x32x16_bf16 v[18:33], v[150:153], v[142:145], v[18:33]
	ds_read_b64_tr_b16 v[208:209], v180 offset:56448
	ds_read_b64_tr_b16 v[210:211], v180 offset:59008
	v_mov_b32_e32 v91, v82
	v_mov_b32_e32 v92, v82
	v_mov_b32_e32 v93, v82
	v_mov_b32_e32 v94, v82
	s_waitcnt lgkmcnt(6)
	v_mfma_f32_32x32x16_bf16 v[2:17], v[146:149], v[142:145], v[2:17]
	ds_read_b64_tr_b16 v[220:221], v180 offset:56512
	ds_read_b64_tr_b16 v[222:223], v180 offset:59072
	v_mov_b32_e32 v95, v82
	v_mov_b32_e32 v96, v82
	v_mov_b32_e32 v97, v82
	s_waitcnt lgkmcnt(6)
	v_mfma_f32_32x32x16_bf16 v[50:65], v[200:203], v[138:141], v[50:65]
	v_exp_f32_e32 v98, v98
	ds_read_b64_tr_b16 v[146:147], v180 offset:61440
	ds_read_b64_tr_b16 v[148:149], v180 offset:64000
	v_exp_f32_e32 v99, v99
	v_add_f32_e32 v142, 0, v98
	v_add_f32_e32 v143, v99, v142
	v_cvt_pk_bf16_f32 v142, v98, v99
	s_waitcnt lgkmcnt(6)
	v_mfma_f32_32x32x16_bf16 v[34:49], v[204:207], v[138:141], v[34:49]
	v_exp_f32_e32 v98, v100
	ds_read_b64_tr_b16 v[200:201], v180 offset:61504
	ds_read_b64_tr_b16 v[202:203], v180 offset:64064
	v_exp_f32_e32 v100, v101
	v_add_f32_e32 v99, v98, v143
	v_add_f32_e32 v144, v100, v99
	v_cvt_pk_bf16_f32 v143, v98, v100
	s_waitcnt lgkmcnt(6)
	v_mfma_f32_32x32x16_bf16 v[18:33], v[208:211], v[138:141], v[18:33]
	ds_read_b64_tr_b16 v[98:99], v180 offset:61568
	ds_read_b64_tr_b16 v[100:101], v180 offset:64128
	v_exp_f32_e32 v102, v102
	s_nop 0
	v_add_f32_e32 v144, v102, v144
	v_exp_f32_e32 v103, v103
	s_waitcnt lgkmcnt(6)
	v_mfma_f32_32x32x16_bf16 v[2:17], v[220:223], v[138:141], v[2:17]
	ds_read_b64_tr_b16 v[204:205], v180 offset:61632
	ds_read_b64_tr_b16 v[206:207], v180 offset:64192
	v_add_f32_e32 v145, v103, v144
	v_cvt_pk_bf16_f32 v144, v102, v103
	v_exp_f32_e32 v102, v104
	s_nop 0
	v_add_f32_e32 v103, v102, v145
	s_waitcnt lgkmcnt(6)
	v_mfma_f32_32x32x16_bf16 v[50:65], v[146:149], v[134:137], v[50:65]
	ds_read_b64_tr_b16 v[208:209], v199 offset:15360
	ds_read_b64_tr_b16 v[210:211], v199 offset:17920
	v_exp_f32_e32 v104, v105
	s_nop 0
	v_add_f32_e32 v138, v104, v103
	v_cvt_pk_bf16_f32 v145, v102, v104
	s_waitcnt lgkmcnt(6)
	v_mfma_f32_32x32x16_bf16 v[34:49], v[200:203], v[134:137], v[34:49]
	v_exp_f32_e32 v106, v106
	ds_read_b64_tr_b16 v[102:103], v199 offset:15424
	ds_read_b64_tr_b16 v[104:105], v199 offset:17984
	v_exp_f32_e32 v107, v107
	v_add_f32_e32 v138, v106, v138
	v_add_f32_e32 v139, v107, v138
	v_cvt_pk_bf16_f32 v138, v106, v107
	s_waitcnt lgkmcnt(6)
	v_mfma_f32_32x32x16_bf16 v[18:33], v[98:101], v[134:137], v[18:33]
	v_exp_f32_e32 v98, v108
	ds_read_b64_tr_b16 v[146:147], v199 offset:15488
	ds_read_b64_tr_b16 v[148:149], v199 offset:18048
	v_exp_f32_e32 v100, v109
	v_add_f32_e32 v99, v98, v139
	v_add_f32_e32 v106, v100, v99
	v_cvt_pk_bf16_f32 v139, v98, v100
	s_waitcnt lgkmcnt(6)
	v_mfma_f32_32x32x16_bf16 v[2:17], v[204:207], v[134:137], v[2:17]
	v_exp_f32_e32 v107, v110
	ds_read_b64_tr_b16 v[98:99], v199 offset:15552
	ds_read_b64_tr_b16 v[100:101], v199 offset:18112
	v_add_f32_e32 v106, v107, v106
	v_exp_f32_e32 v108, v111
	s_waitcnt lgkmcnt(6)
	v_mfma_f32_32x32x16_bf16 v[50:65], v[208:211], v[130:133], v[50:65]
	ds_read_b128 v[200:203], v196
	v_cvt_pk_bf16_f32 v140, v107, v108
	v_exp_f32_e32 v107, v112
	v_add_f32_e32 v106, v108, v106
	v_add_f32_e32 v106, v107, v106
	s_waitcnt lgkmcnt(5)
	v_mfma_f32_32x32x16_bf16 v[34:49], v[102:105], v[130:133], v[34:49]
	v_exp_f32_e32 v108, v113
	ds_read_b128 v[204:207], v196 offset:8704
	v_add_f32_e32 v106, v108, v106
	v_cvt_pk_bf16_f32 v141, v107, v108
	s_waitcnt lgkmcnt(4)
	v_mfma_f32_32x32x16_bf16 v[18:33], v[146:149], v[130:133], v[18:33]
	v_exp_f32_e32 v66, v66
	v_exp_f32_e32 v67, v67
	ds_read_b128 v[208:211], v196 offset:32
	v_add_f32_e32 v102, v66, v106
	v_add_f32_e32 v102, v67, v102
	v_cvt_pk_bf16_f32 v134, v66, v67
	s_waitcnt lgkmcnt(3)
	v_mfma_f32_32x32x16_bf16 v[2:17], v[98:101], v[130:133], v[2:17]
	v_exp_f32_e32 v66, v68
	ds_read_b128 v[146:149], v196 offset:8736
	v_exp_f32_e32 v68, v69
	v_add_f32_e32 v67, v66, v102
	v_add_f32_e32 v98, v68, v67
	v_cvt_pk_bf16_f32 v135, v66, v68
	v_exp_f32_e32 v70, v70
	ds_read_b128 v[66:69], v196 offset:64
	v_add_f32_e32 v130, v70, v98
	s_waitcnt lgkmcnt(4)
	v_mfma_f32_32x32x16_bf16 v[98:113], v[200:203], v[114:117], v[82:97]
	s_waitcnt lgkmcnt(3)
	v_mfma_f32_32x32x16_bf16 v[82:97], v[204:207], v[114:117], v[82:97]
	v_exp_f32_e32 v71, v71
	ds_read_b128 v[200:203], v196 offset:8768
	v_cvt_pk_bf16_f32 v136, v70, v71
	v_exp_f32_e32 v70, v72
	v_add_f32_e32 v130, v71, v130
	v_add_f32_e32 v71, v70, v130
	s_waitcnt lgkmcnt(3)
	v_mfma_f32_32x32x16_bf16 v[98:113], v[208:211], v[118:121], v[98:113]
	v_exp_f32_e32 v72, v73
	ds_read_b128 v[204:207], v196 offset:96
	v_add_f32_e32 v130, v72, v71
	v_cvt_pk_bf16_f32 v137, v70, v72
	s_waitcnt lgkmcnt(3)
	v_mfma_f32_32x32x16_bf16 v[82:97], v[146:149], v[118:121], v[82:97]
	v_exp_f32_e32 v74, v74
	v_exp_f32_e32 v75, v75
	ds_read_b128 v[70:73], v196 offset:8800
	v_add_f32_e32 v130, v74, v130
	v_add_f32_e32 v131, v75, v130
	v_cvt_pk_bf16_f32 v130, v74, v75
	s_waitcnt lgkmcnt(3)
	v_mfma_f32_32x32x16_bf16 v[98:113], v[66:69], v[122:125], v[98:113]
	v_exp_f32_e32 v66, v76
	v_exp_f32_e32 v68, v77
	s_waitcnt vmcnt(3)
	ds_write_b128 v190, v[228:231] offset:25600
	s_waitcnt vmcnt(2)
	ds_write_b128 v188, v[232:235] offset:25600
	v_add_f32_e32 v67, v66, v131
	v_cvt_pk_bf16_f32 v131, v66, v68
	v_add_f32_e32 v67, v68, v67
	s_waitcnt lgkmcnt(4)
	v_mfma_f32_32x32x16_bf16 v[82:97], v[200:203], v[122:125], v[82:97]
	v_exp_f32_e32 v66, v78
	s_nop 0
	v_add_f32_e32 v67, v66, v67
	s_waitcnt lgkmcnt(3)
	v_mfma_f32_32x32x16_bf16 v[98:113], v[204:207], v[126:129], v[98:113]
	v_exp_f32_e32 v68, v79
	s_nop 0
	v_cvt_pk_bf16_f32 v132, v66, v68
	v_exp_f32_e32 v66, v80
	v_add_f32_e32 v67, v68, v67
	v_add_u32_e32 v68, s37, v176
	s_waitcnt vmcnt(1)
	ds_write_b128 v68, v[236:239] offset:51200
	v_add_u32_e32 v68, s37, v178
	v_add_f32_e32 v67, v66, v67
	s_waitcnt vmcnt(0)
	ds_write_b128 v68, v[240:243] offset:51200
	s_cmpk_lt_u32 s76, 0x7f
	s_cselect_b32 s84, 0x4d000, 0
	s_add_u32 s84, s84, s88
	s_add_u32 s84, s8, s84
	s_addc_u32 s85, s9, 0
	s_add_u32 s98, s8, s88
	s_addc_u32 s99, s9, 0
	global_load_dwordx4 v[228:231], v168, s[84:85] offset:1024
	global_load_dwordx4 v[232:235], v170, s[84:85] offset:1024
	global_load_dwordx4 v[236:239], v168, s[98:99] offset:2048
	global_load_dwordx4 v[240:243], v170, s[98:99] offset:2048
	s_waitcnt lgkmcnt(4)
	v_mfma_f32_32x32x16_bf16 v[82:97], v[70:73], v[126:129], v[82:97]
	v_exp_f32_e32 v68, v81
	s_nop 0
	v_add_f32_e32 v199, v68, v67
	v_cvt_pk_bf16_f32 v133, v66, v68
	s_mul_i32 s37, s77, 0x5000
	v_add_u32_e32 v201, s37, v192
	ds_read_b64_tr_b16 v[158:159], v201 offset:51200
	ds_read_b64_tr_b16 v[154:155], v201 offset:51264
	ds_read_b64_tr_b16 v[150:151], v201 offset:51328
	ds_read_b64_tr_b16 v[146:147], v201 offset:51392
	ds_read_b64_tr_b16 v[160:161], v201 offset:53760
	ds_read_b64_tr_b16 v[156:157], v201 offset:53824
	ds_read_b64_tr_b16 v[152:153], v201 offset:53888
	ds_read_b64_tr_b16 v[148:149], v201 offset:53952
	s_andn2_b64 vcc, exec, s[6:7]
	v_add_u32_e32 v200, s75, v179
	s_cbranch_vccnz .LBB0_987
	v_add_u32_e32 v66, 0x80, v200
	v_med3_i32 v67, v66, 0, v216
	v_med3_i32 v66, v66, s46, v217
	v_lshl_add_u32 v68, v66, 2, s15
	v_add_u32_e32 v66, 0x81, v200
	v_med3_i32 v69, v66, 0, v216
	v_med3_i32 v66, v66, s46, v217
	v_lshl_add_u32 v70, v66, 2, s15
	v_add_u32_e32 v66, 0x82, v200
	v_med3_i32 v71, v66, 0, v216
	v_med3_i32 v66, v66, s46, v217
	v_lshl_add_u32 v72, v66, 2, s15
	v_add_u32_e32 v66, 0x83, v200
	v_med3_i32 v73, v66, 0, v216
	v_med3_i32 v66, v66, s46, v217
	v_lshl_add_u32 v67, v67, 2, s15
	v_lshl_add_u32 v69, v69, 2, s15
	v_lshl_add_u32 v71, v71, 2, s15
	v_lshl_add_u32 v73, v73, 2, s15
	v_lshl_add_u32 v74, v66, 2, s15
	ds_read_b32 v66, v67
	ds_read_b32 v68, v68 offset:128
	ds_read_b32 v67, v69
	ds_read_b32 v69, v70 offset:128
	ds_read_b32 v70, v71
	ds_read_b32 v72, v72 offset:128
	ds_read_b32 v71, v73
	ds_read_b32 v73, v74 offset:128
	v_add_u32_e32 v74, 0x88, v200
	v_med3_i32 v75, v74, 0, v216
	v_med3_i32 v74, v74, s46, v217
	v_lshl_add_u32 v76, v74, 2, s15
	v_add_u32_e32 v74, 0x89, v200
	v_med3_i32 v77, v74, 0, v216
	v_med3_i32 v74, v74, s46, v217
	v_lshl_add_u32 v78, v74, 2, s15
	v_add_u32_e32 v74, 0x8a, v200
	v_med3_i32 v79, v74, 0, v216
	v_med3_i32 v74, v74, s46, v217
	v_lshl_add_u32 v80, v74, 2, s15
	v_add_u32_e32 v74, 0x8b, v200
	v_med3_i32 v81, v74, 0, v216
	v_med3_i32 v74, v74, s46, v217
	v_lshl_add_u32 v75, v75, 2, s15
	v_lshl_add_u32 v77, v77, 2, s15
	v_lshl_add_u32 v79, v79, 2, s15
	v_lshl_add_u32 v81, v81, 2, s15
	v_lshl_add_u32 v162, v74, 2, s15
	ds_read_b32 v74, v75
	ds_read_b32 v76, v76 offset:128
	ds_read_b32 v75, v77
	ds_read_b32 v77, v78 offset:128
	ds_read_b32 v78, v79
	ds_read_b32 v80, v80 offset:128
	ds_read_b32 v79, v81
	ds_read_b32 v81, v162 offset:128
	v_add_u32_e32 v162, 0x90, v200
	v_med3_i32 v163, v162, 0, v216
	v_med3_i32 v162, v162, s46, v217
	v_lshl_add_u32 v164, v162, 2, s15
	v_add_u32_e32 v162, 0x91, v200
	v_med3_i32 v165, v162, 0, v216
	v_med3_i32 v162, v162, s46, v217
	v_lshl_add_u32 v180, v162, 2, s15
	v_add_u32_e32 v162, 0x92, v200
	v_med3_i32 v202, v162, 0, v216
	v_med3_i32 v162, v162, s46, v217
	v_add_u32_e32 v207, 0x99, v200
	v_lshl_add_u32 v203, v162, 2, s15
	v_add_u32_e32 v162, 0x93, v200
	v_med3_i32 v208, v207, 0, v216
	v_med3_i32 v207, v207, s46, v217
	v_med3_i32 v204, v162, 0, v216
	v_lshl_add_u32 v214, v207, 2, s15
	v_add_u32_e32 v207, 0x9a, v200
	v_lshl_add_u32 v163, v163, 2, s15
	v_lshl_add_u32 v165, v165, 2, s15
	v_lshl_add_u32 v202, v202, 2, s15
	v_med3_i32 v162, v162, s46, v217
	v_lshl_add_u32 v205, v204, 2, s15
	v_lshl_add_u32 v209, v208, 2, s15
	v_med3_i32 v208, v207, 0, v216
	v_med3_i32 v207, v207, s46, v217
	v_lshl_add_u32 v206, v162, 2, s15
	ds_read_b32 v162, v163
	ds_read_b32 v164, v164 offset:128
	ds_read_b32 v163, v165
	ds_read_b32 v165, v180 offset:128
	ds_read_b32 v202, v202
	ds_read_b32 v204, v203 offset:128
	ds_read_b32 v203, v205
	ds_read_b32 v205, v206 offset:128
	v_add_u32_e32 v180, 0x98, v200
	v_lshl_add_u32 v212, v207, 2, s15
	v_add_u32_e32 v207, 0x9b, v200
	v_med3_i32 v206, v180, 0, v216
	v_lshl_add_u32 v210, v208, 2, s15
	v_med3_i32 v208, v207, 0, v216
	v_med3_i32 v207, v207, s46, v217
	v_med3_i32 v180, v180, s46, v217
	v_lshl_add_u32 v206, v206, 2, s15
	v_lshl_add_u32 v211, v208, 2, s15
	v_lshl_add_u32 v213, v207, 2, s15
	v_lshl_add_u32 v180, v180, 2, s15
	ds_read_b32 v206, v206
	ds_read_b32 v208, v180 offset:128
	ds_read_b32 v210, v210
	ds_read_b32 v211, v211
	ds_read_b32 v207, v209
	ds_read_b32 v213, v213 offset:128
	ds_read_b32 v212, v212 offset:128
	ds_read_b32 v209, v214 offset:128
	s_waitcnt lgkmcnt(4)
	v_pk_add_f32 v[112:113], v[112:113], v[210:211]
	s_waitcnt lgkmcnt(3)
	v_pk_add_f32 v[110:111], v[110:111], v[206:207]
	v_pk_add_f32 v[108:109], v[108:109], v[202:203]
	v_pk_add_f32 v[106:107], v[106:107], v[162:163]
	v_pk_add_f32 v[104:105], v[104:105], v[78:79]
	v_pk_add_f32 v[102:103], v[102:103], v[74:75]
	v_pk_add_f32 v[100:101], v[100:101], v[70:71]
	v_pk_add_f32 v[98:99], v[98:99], v[66:67]
	s_waitcnt lgkmcnt(1)
	v_pk_add_f32 v[96:97], v[96:97], v[212:213]
	s_waitcnt lgkmcnt(0)
	v_pk_add_f32 v[94:95], v[94:95], v[208:209]
	v_pk_add_f32 v[92:93], v[92:93], v[204:205]
	v_pk_add_f32 v[90:91], v[90:91], v[164:165]
	v_pk_add_f32 v[88:89], v[88:89], v[80:81]
	v_pk_add_f32 v[86:87], v[86:87], v[76:77]
	v_pk_add_f32 v[84:85], v[84:85], v[72:73]
	v_pk_add_f32 v[82:83], v[82:83], v[68:69]

.LBB0_992:
	v_mfma_f32_32x32x16_bf16 v[50:65], v[158:161], v[142:145], v[50:65]
	s_cmpk_lt_i32 s36, 0x5b
	s_cselect_b64 s[36:37], -1, 0
	s_add_i32 s6, s75, 0xffffff40
	s_addk_i32 s52, 0xff40
	s_cmpk_lt_i32 s52, 0xfea7
	s_cselect_b64 s[4:5], -1, 0
	s_cmp_gt_i32 s6, s71
	s_cselect_b64 s[6:7], -1, 0
	v_add_u32_e32 v210, 0xc800, v201
	s_cmpk_gt_u32 s76, 0x7e
	s_cselect_b64 s[52:53], -1, 0
	ds_read_b64_tr_b16 v[202:203], v201 offset:56320
	ds_read_b64_tr_b16 v[204:205], v201 offset:58880
	s_mul_i32 s79, s74, 0x5000
	s_add_i32 s79, s79, 0
	v_mov_b32_e32 v68, v67
	v_mov_b32_e32 v69, v67
	v_mov_b32_e32 v70, v67
	v_mov_b32_e32 v71, v67
	v_mfma_f32_32x32x16_bf16 v[34:49], v[154:157], v[142:145], v[34:49]
	ds_read_b64_tr_b16 v[206:207], v201 offset:56384
	ds_read_b64_tr_b16 v[208:209], v201 offset:58944
	v_mov_b32_e32 v72, v67
	v_mov_b32_e32 v73, v67
	v_mov_b32_e32 v74, v67
	v_mov_b32_e32 v75, v67
	ds_read_b64_tr_b16 v[220:221], v201 offset:56448
	ds_read_b64_tr_b16 v[222:223], v201 offset:59008
	v_mfma_f32_32x32x16_bf16 v[18:33], v[150:153], v[142:145], v[18:33]
	v_mov_b32_e32 v76, v67
	v_mov_b32_e32 v77, v67
	v_mov_b32_e32 v78, v67
	v_mov_b32_e32 v79, v67
	v_mfma_f32_32x32x16_bf16 v[2:17], v[146:149], v[142:145], v[2:17]
	ds_read_b64_tr_b16 v[182:183], v201 offset:56512
	ds_read_b64_tr_b16 v[184:185], v201 offset:59072
	v_mov_b32_e32 v80, v67
	v_mov_b32_e32 v81, v67
	s_waitcnt lgkmcnt(6)
	v_mfma_f32_32x32x16_bf16 v[50:65], v[202:205], v[138:141], v[50:65]
	v_exp_f32_e32 v98, v98
	ds_read_b64_tr_b16 v[146:147], v201 offset:61440
	ds_read_b64_tr_b16 v[148:149], v201 offset:64000
	v_exp_f32_e32 v99, v99
	v_add_f32_e32 v142, 0, v98
	v_add_f32_e32 v143, v99, v142
	v_cvt_pk_bf16_f32 v142, v98, v99
	s_waitcnt lgkmcnt(6)
	v_mfma_f32_32x32x16_bf16 v[34:49], v[206:209], v[138:141], v[34:49]
	v_exp_f32_e32 v98, v100
	ds_read_b64_tr_b16 v[202:203], v201 offset:61504
	ds_read_b64_tr_b16 v[204:205], v201 offset:64064
	v_exp_f32_e32 v100, v101
	v_add_f32_e32 v99, v98, v143
	v_add_f32_e32 v144, v100, v99
	v_cvt_pk_bf16_f32 v143, v98, v100
	s_waitcnt lgkmcnt(6)
	v_mfma_f32_32x32x16_bf16 v[18:33], v[220:223], v[138:141], v[18:33]
	ds_read_b64_tr_b16 v[98:99], v201 offset:61568
	ds_read_b64_tr_b16 v[100:101], v201 offset:64128
	v_exp_f32_e32 v102, v102
	s_nop 0
	v_add_f32_e32 v144, v102, v144
	v_exp_f32_e32 v103, v103
	s_waitcnt lgkmcnt(6)
	v_mfma_f32_32x32x16_bf16 v[2:17], v[182:185], v[138:141], v[2:17]
	ds_read_b64_tr_b16 v[206:207], v201 offset:61632
	ds_read_b64_tr_b16 v[208:209], v201 offset:64192
	v_add_f32_e32 v145, v103, v144
	v_cvt_pk_bf16_f32 v144, v102, v103
	v_exp_f32_e32 v102, v104
	s_nop 0
	v_add_f32_e32 v103, v102, v145
	s_waitcnt lgkmcnt(6)
	v_mfma_f32_32x32x16_bf16 v[50:65], v[146:149], v[134:137], v[50:65]
	ds_read_b64_tr_b16 v[182:183], v210 offset:15360
	ds_read_b64_tr_b16 v[184:185], v210 offset:17920
	v_exp_f32_e32 v104, v105
	s_nop 0
	v_add_f32_e32 v138, v104, v103
	v_cvt_pk_bf16_f32 v145, v102, v104
	s_waitcnt lgkmcnt(6)
	v_mfma_f32_32x32x16_bf16 v[34:49], v[202:205], v[134:137], v[34:49]
	v_exp_f32_e32 v106, v106
	ds_read_b64_tr_b16 v[102:103], v210 offset:15424
	ds_read_b64_tr_b16 v[104:105], v210 offset:17984
	v_exp_f32_e32 v107, v107
	v_add_f32_e32 v138, v106, v138
	v_add_f32_e32 v139, v107, v138
	v_cvt_pk_bf16_f32 v138, v106, v107
	s_waitcnt lgkmcnt(6)
	v_mfma_f32_32x32x16_bf16 v[18:33], v[98:101], v[134:137], v[18:33]
	v_exp_f32_e32 v98, v108
	ds_read_b64_tr_b16 v[146:147], v210 offset:15488
	ds_read_b64_tr_b16 v[148:149], v210 offset:18048
	v_exp_f32_e32 v100, v109
	v_add_f32_e32 v99, v98, v139
	v_add_f32_e32 v106, v100, v99
	v_cvt_pk_bf16_f32 v139, v98, v100
	s_waitcnt lgkmcnt(6)
	v_mfma_f32_32x32x16_bf16 v[2:17], v[206:209], v[134:137], v[2:17]
	v_exp_f32_e32 v107, v110
	ds_read_b64_tr_b16 v[98:99], v210 offset:15552
	ds_read_b64_tr_b16 v[100:101], v210 offset:18112
	v_add_f32_e32 v106, v107, v106
	v_exp_f32_e32 v108, v111
	s_waitcnt lgkmcnt(6)
	v_mfma_f32_32x32x16_bf16 v[50:65], v[182:185], v[130:133], v[50:65]
	ds_read_b128 v[202:205], v196 offset:25600
	v_cvt_pk_bf16_f32 v140, v107, v108
	v_exp_f32_e32 v107, v112
	v_add_f32_e32 v106, v108, v106
	v_add_f32_e32 v106, v107, v106
	s_waitcnt lgkmcnt(5)
	v_mfma_f32_32x32x16_bf16 v[34:49], v[102:105], v[130:133], v[34:49]
	v_exp_f32_e32 v108, v113
	ds_read_b128 v[182:185], v196 offset:34304
	v_add_f32_e32 v106, v108, v106
	v_cvt_pk_bf16_f32 v141, v107, v108
	s_waitcnt lgkmcnt(4)
	v_mfma_f32_32x32x16_bf16 v[18:33], v[146:149], v[130:133], v[18:33]
	v_exp_f32_e32 v82, v82
	v_exp_f32_e32 v83, v83
	ds_read_b128 v[206:209], v196 offset:25632
	v_add_f32_e32 v102, v82, v106
	v_add_f32_e32 v102, v83, v102
	v_cvt_pk_bf16_f32 v134, v82, v83
	s_waitcnt lgkmcnt(3)
	v_mfma_f32_32x32x16_bf16 v[2:17], v[98:101], v[130:133], v[2:17]
	v_exp_f32_e32 v82, v84
	ds_read_b128 v[146:149], v196 offset:34336
	v_exp_f32_e32 v84, v85
	v_add_f32_e32 v83, v82, v102
	v_add_f32_e32 v98, v84, v83
	v_cvt_pk_bf16_f32 v135, v82, v84
	v_exp_f32_e32 v86, v86
	ds_read_b128 v[82:85], v196 offset:25664
	v_add_f32_e32 v130, v86, v98
	s_waitcnt lgkmcnt(4)
	v_mfma_f32_32x32x16_bf16 v[98:113], v[202:205], v[114:117], v[66:81]
	s_waitcnt lgkmcnt(3)
	v_mfma_f32_32x32x16_bf16 v[66:81], v[182:185], v[114:117], v[66:81]
	v_exp_f32_e32 v87, v87
	ds_read_b128 v[202:205], v196 offset:34368
	v_cvt_pk_bf16_f32 v136, v86, v87
	v_exp_f32_e32 v86, v88
	v_add_f32_e32 v130, v87, v130
	v_add_f32_e32 v87, v86, v130
	s_waitcnt lgkmcnt(3)
	v_mfma_f32_32x32x16_bf16 v[98:113], v[206:209], v[118:121], v[98:113]
	v_exp_f32_e32 v88, v89
	ds_read_b128 v[182:185], v196 offset:25696
	v_add_f32_e32 v130, v88, v87
	v_cvt_pk_bf16_f32 v137, v86, v88
	s_waitcnt lgkmcnt(3)
	v_mfma_f32_32x32x16_bf16 v[66:81], v[146:149], v[118:121], v[66:81]
	v_exp_f32_e32 v90, v90
	v_exp_f32_e32 v91, v91
	ds_read_b128 v[86:89], v196 offset:34400
	v_add_f32_e32 v130, v90, v130
	v_add_f32_e32 v131, v91, v130
	v_cvt_pk_bf16_f32 v130, v90, v91
	s_waitcnt lgkmcnt(3)
	v_mfma_f32_32x32x16_bf16 v[98:113], v[82:85], v[122:125], v[98:113]
	v_exp_f32_e32 v82, v92
	v_exp_f32_e32 v84, v93
	s_waitcnt vmcnt(3)
	ds_write_b128 v190, v[228:231]
	s_waitcnt vmcnt(2)
	ds_write_b128 v188, v[232:235]
	v_add_f32_e32 v83, v82, v131
	v_cvt_pk_bf16_f32 v131, v82, v84
	v_add_f32_e32 v83, v84, v83
	s_waitcnt lgkmcnt(4)
	v_mfma_f32_32x32x16_bf16 v[66:81], v[202:205], v[122:125], v[66:81]
	v_exp_f32_e32 v82, v94
	s_nop 0
	v_add_f32_e32 v83, v82, v83
	s_waitcnt lgkmcnt(3)
	v_mfma_f32_32x32x16_bf16 v[98:113], v[182:185], v[126:129], v[98:113]
	v_exp_f32_e32 v84, v95
	s_nop 0
	v_cvt_pk_bf16_f32 v132, v82, v84
	v_exp_f32_e32 v82, v96
	v_add_f32_e32 v83, v84, v83
	v_add_u32_e32 v84, s79, v176
	s_waitcnt vmcnt(1)
	ds_write_b128 v84, v[236:239] offset:51200
	v_add_u32_e32 v84, s79, v178
	v_add_f32_e32 v83, v82, v83
	s_waitcnt vmcnt(0)
	ds_write_b128 v84, v[240:243] offset:51200
	s_cmpk_lt_u32 s76, 0x7f
	s_cselect_b32 s84, s67, 0
	s_cselect_b32 s98, 0x4d000, 0
	s_add_u32 s84, s84, s88
	s_add_u32 s98, s98, s88
	s_add_u32 s84, s8, s84
	s_addc_u32 s85, s9, 0
	s_add_u32 s98, s8, s98
	s_addc_u32 s99, s9, 0
	global_load_dwordx4 v[228:231], v168, s[84:85] offset:1024
	global_load_dwordx4 v[232:235], v170, s[84:85] offset:1024
	global_load_dwordx4 v[236:239], v168, s[98:99] offset:2048
	global_load_dwordx4 v[240:243], v170, s[98:99] offset:2048
	s_waitcnt lgkmcnt(4)
	v_mfma_f32_32x32x16_bf16 v[66:81], v[86:89], v[126:129], v[66:81]
	v_exp_f32_e32 v84, v97
	s_nop 0
	v_add_f32_e32 v163, v84, v83
	v_cvt_pk_bf16_f32 v133, v82, v84
	v_add_u32_e32 v82, s78, v192
	ds_read_b64_tr_b16 v[158:159], v82 offset:51200
	ds_read_b64_tr_b16 v[154:155], v82 offset:51264
	ds_read_b64_tr_b16 v[150:151], v82 offset:51328
	ds_read_b64_tr_b16 v[146:147], v82 offset:51392
	ds_read_b64_tr_b16 v[160:161], v82 offset:53760
	ds_read_b64_tr_b16 v[156:157], v82 offset:53824
	ds_read_b64_tr_b16 v[152:153], v82 offset:53888
	ds_read_b64_tr_b16 v[148:149], v82 offset:53952
	s_and_b64 s[0:1], s[0:1], s[36:37]
	s_andn2_b64 vcc, exec, s[0:1]
	s_cbranch_vccnz .LBB0_994
	v_add_u32_e32 v82, 0xc0, v200
	v_med3_i32 v83, v82, 0, v216
	v_med3_i32 v82, v82, s46, v217
	v_lshl_add_u32 v84, v82, 2, s15
	v_add_u32_e32 v82, 0xc1, v200
	v_med3_i32 v85, v82, 0, v216
	v_med3_i32 v82, v82, s46, v217
	v_lshl_add_u32 v86, v82, 2, s15
	v_add_u32_e32 v82, 0xc2, v200
	v_med3_i32 v87, v82, 0, v216
	v_med3_i32 v82, v82, s46, v217
	v_lshl_add_u32 v88, v82, 2, s15
	v_add_u32_e32 v82, 0xc3, v200
	v_med3_i32 v89, v82, 0, v216
	v_med3_i32 v82, v82, s46, v217
	v_lshl_add_u32 v83, v83, 2, s15
	v_lshl_add_u32 v85, v85, 2, s15
	v_lshl_add_u32 v87, v87, 2, s15
	v_lshl_add_u32 v89, v89, 2, s15
	v_lshl_add_u32 v90, v82, 2, s15
	ds_read_b32 v82, v83
	ds_read_b32 v84, v84 offset:128
	ds_read_b32 v83, v85
	ds_read_b32 v85, v86 offset:128
	ds_read_b32 v86, v87
	ds_read_b32 v88, v88 offset:128
	ds_read_b32 v87, v89
	ds_read_b32 v89, v90 offset:128
	v_add_u32_e32 v90, 0xc8, v200
	v_med3_i32 v91, v90, 0, v216
	v_med3_i32 v90, v90, s46, v217
	v_lshl_add_u32 v92, v90, 2, s15
	v_add_u32_e32 v90, 0xc9, v200
	v_med3_i32 v93, v90, 0, v216
	v_med3_i32 v90, v90, s46, v217
	v_lshl_add_u32 v94, v90, 2, s15
	v_add_u32_e32 v90, 0xca, v200
	v_med3_i32 v95, v90, 0, v216
	v_med3_i32 v90, v90, s46, v217
	v_add_u32_e32 v165, 0xd1, v200
	v_lshl_add_u32 v96, v90, 2, s15
	v_add_u32_e32 v90, 0xcb, v200
	v_med3_i32 v182, v165, 0, v216
	v_med3_i32 v165, v165, s46, v217
	v_med3_i32 v97, v90, 0, v216
	v_med3_i32 v90, v90, s46, v217
	v_lshl_add_u32 v184, v165, 2, s15
	v_add_u32_e32 v165, 0xd2, v200
	v_lshl_add_u32 v91, v91, 2, s15
	v_lshl_add_u32 v93, v93, 2, s15
	v_lshl_add_u32 v95, v95, 2, s15
	v_lshl_add_u32 v97, v97, 2, s15
	v_lshl_add_u32 v162, v90, 2, s15
	v_lshl_add_u32 v183, v182, 2, s15
	v_med3_i32 v182, v165, 0, v216
	v_med3_i32 v165, v165, s46, v217
	ds_read_b32 v90, v91
	ds_read_b32 v92, v92 offset:128
	ds_read_b32 v91, v93
	ds_read_b32 v93, v94 offset:128
	ds_read_b32 v94, v95
	ds_read_b32 v96, v96 offset:128
	ds_read_b32 v95, v97
	ds_read_b32 v97, v162 offset:128
	v_add_u32_e32 v162, 0xd0, v200
	v_lshl_add_u32 v201, v165, 2, s15
	v_add_u32_e32 v165, 0xd3, v200
	v_med3_i32 v164, v162, 0, v216
	v_lshl_add_u32 v185, v182, 2, s15
	v_med3_i32 v182, v165, 0, v216
	v_med3_i32 v165, v165, s46, v217
	v_med3_i32 v162, v162, s46, v217
	v_lshl_add_u32 v164, v164, 2, s15
	v_lshl_add_u32 v203, v182, 2, s15
	v_lshl_add_u32 v204, v165, 2, s15
	v_lshl_add_u32 v162, v162, 2, s15
	ds_read_b32 v164, v164
	ds_read_b32 v182, v162 offset:128
	ds_read_b32 v165, v183
	ds_read_b32 v183, v184 offset:128
	ds_read_b32 v184, v185
	ds_read_b32 v202, v201 offset:128
	ds_read_b32 v185, v203
	ds_read_b32 v203, v204 offset:128
	v_add_u32_e32 v204, 0xd9, v200
	v_med3_i32 v205, v204, 0, v216
	v_med3_i32 v204, v204, s46, v217
	v_lshl_add_u32 v210, v204, 2, s15
	v_add_u32_e32 v204, 0xda, v200
	v_add_u32_e32 v162, 0xd8, v200
	v_med3_i32 v206, v204, 0, v216
	v_med3_i32 v204, v204, s46, v217
	v_add_u32_e32 v200, 0xdb, v200
	v_med3_i32 v201, v162, 0, v216
	v_lshl_add_u32 v208, v204, 2, s15
	v_med3_i32 v204, v200, 0, v216
	v_med3_i32 v200, v200, s46, v217
	v_med3_i32 v162, v162, s46, v217
	v_lshl_add_u32 v201, v201, 2, s15
	v_lshl_add_u32 v205, v205, 2, s15
	v_lshl_add_u32 v206, v206, 2, s15
	v_lshl_add_u32 v207, v204, 2, s15
	v_lshl_add_u32 v209, v200, 2, s15
	v_lshl_add_u32 v162, v162, 2, s15
	ds_read_b32 v200, v201
	ds_read_b32 v204, v162 offset:128
	ds_read_b32 v206, v206
	ds_read_b32 v207, v207
	ds_read_b32 v201, v205
	ds_read_b32 v209, v209 offset:128
	ds_read_b32 v208, v208 offset:128
	ds_read_b32 v205, v210 offset:128
	s_waitcnt lgkmcnt(4)
	v_pk_add_f32 v[112:113], v[112:113], v[206:207]
	s_waitcnt lgkmcnt(3)
	v_pk_add_f32 v[110:111], v[110:111], v[200:201]
	v_pk_add_f32 v[108:109], v[108:109], v[184:185]
	v_pk_add_f32 v[106:107], v[106:107], v[164:165]
	v_pk_add_f32 v[104:105], v[104:105], v[94:95]
	v_pk_add_f32 v[102:103], v[102:103], v[90:91]
	v_pk_add_f32 v[100:101], v[100:101], v[86:87]
	v_pk_add_f32 v[98:99], v[98:99], v[82:83]
	s_waitcnt lgkmcnt(1)
	v_pk_add_f32 v[80:81], v[80:81], v[208:209]
	s_waitcnt lgkmcnt(0)
	v_pk_add_f32 v[78:79], v[78:79], v[204:205]
	v_pk_add_f32 v[76:77], v[76:77], v[202:203]
	v_pk_add_f32 v[74:75], v[74:75], v[182:183]
	v_pk_add_f32 v[72:73], v[72:73], v[96:97]
	v_pk_add_f32 v[70:71], v[70:71], v[92:93]
	v_pk_add_f32 v[68:69], v[68:69], v[88:89]
	v_pk_add_f32 v[66:67], v[66:67], v[84:85]
